# v52 + far-block cleanup: removed redundant lgkmcnt(4), no-op s_add and the WAR pad that guarded the deleted subs
# baseline (speedup 1.0000x reference)
.Lfar_a2:
	s_lshl_b32 s13, s29, 6
	s_mul_i32 s12, s29, 0x2200
	v_add_u32_e32 v171, s12, v139
	ds_read_b128 v[222:225], v171 offset:1024
	ds_read_b128 v[226:229], v171 offset:1088
	ds_read_b128 v[230:233], v171 offset:2112
	ds_read_b128 v[234:237], v171 offset:2176
	s_waitcnt lgkmcnt(3)
	v_mfma_f32_16x16x32_bf16 v[222:225], v[222:225], v[4:7], v[252:255]
	s_waitcnt lgkmcnt(1)
	v_mfma_f32_16x16x32_bf16 v[230:233], v[230:233], v[4:7], v[252:255]
	v_mfma_f32_16x16x32_bf16 v[222:225], v[226:229], v[8:11], v[222:225]
	ds_read_b128 v[226:229], v171 offset:1152
	ds_read_b128 v[238:241], v171 offset:1216
	s_waitcnt lgkmcnt(2)
	v_mfma_f32_16x16x32_bf16 v[230:233], v[234:237], v[8:11], v[230:233]
	ds_read_b128 v[234:237], v171 offset:2240
	ds_read_b128 v[242:245], v171 offset:2304
	s_nop 2
	v_exp_f32_e32 v3, v223
	v_exp_f32_e32 v219, v225
	s_waitcnt lgkmcnt(3)
	v_mfma_f32_16x16x32_bf16 v[226:229], v[226:229], v[12:15], v[252:255]
	v_exp_f32_e32 v225, v231
	s_waitcnt lgkmcnt(2)
	v_mfma_f32_16x16x32_bf16 v[226:229], v[238:241], v[16:19], v[226:229]
	v_add3_u32 v0, s13, v134, v135
	v_exp_f32_e32 v217, v224
	s_waitcnt lgkmcnt(1)
	v_mfma_f32_16x16x32_bf16 v[172:175], v[234:237], v[12:15], v[252:255]
	ds_read_b128 v[234:237], v0 offset:18432
	ds_read_b128 v[238:241], v0 offset:20736
	s_nop 1
	v_exp_f32_e32 v2, v226
	v_exp_f32_e32 v171, v227
	s_waitcnt lgkmcnt(2)
	v_mfma_f32_16x16x32_bf16 v[172:175], v[242:245], v[16:19], v[172:175]
	ds_read_b128 v[242:245], v0 offset:23040
	ds_read_b128 v[246:249], v0 offset:25344
	v_exp_f32_e32 v0, v222
	v_exp_f32_e32 v218, v228
	v_exp_f32_e32 v223, v229
	v_exp_f32_e32 v222, v230
	s_nop 1
	v_exp_f32_e32 v224, v172
	v_exp_f32_e32 v226, v173
	v_exp_f32_e32 v227, v232
	v_exp_f32_e32 v228, v174
	v_exp_f32_e32 v229, v233
	v_exp_f32_e32 v230, v175
	v_cvt_pk_bf16_f32 v172, v0, v3
	v_cvt_pk_bf16_f32 v173, v217, v219
	v_cvt_pk_bf16_f32 v174, v222, v225
	v_cvt_pk_bf16_f32 v175, v227, v229
	v_cvt_pk_bf16_f32 v222, v2, v171
	v_cvt_pk_bf16_f32 v223, v218, v223
	v_cvt_pk_bf16_f32 v224, v224, v226
	v_cvt_pk_bf16_f32 v225, v228, v230
	v_add3_u32 v0, s13, v135, v134
	s_waitcnt lgkmcnt(3)
	v_mfma_f32_16x16x32_bf16 v[104:107], v[234:237], v[172:175], v[104:107]
	ds_read_b128 v[226:229], v0 offset:27648
	ds_read_b128 v[230:233], v0 offset:29952
	v_mfma_f32_16x16x32_bf16 v[112:115], v[234:237], v[222:225], v[112:115]
	ds_read_b128 v[234:237], v0 offset:32256
	s_waitcnt lgkmcnt(5)
	v_mfma_f32_16x16x32_bf16 v[100:103], v[238:241], v[172:175], v[100:103]
	v_mfma_f32_16x16x32_bf16 v[108:111], v[238:241], v[222:225], v[108:111]
	ds_read_b128 v[238:241], v0 offset:34560
	s_waitcnt lgkmcnt(5)
	v_mfma_f32_16x16x32_bf16 v[88:91], v[242:245], v[172:175], v[88:91]
	v_mfma_f32_16x16x32_bf16 v[96:99], v[242:245], v[222:225], v[96:99]
	v_mfma_f32_16x16x32_bf16 v[84:87], v[246:249], v[172:175], v[84:87]
	v_mfma_f32_16x16x32_bf16 v[92:95], v[246:249], v[222:225], v[92:95]
	s_mov_b32 s66, s64
	s_mov_b32 s67, s64
	s_waitcnt lgkmcnt(3)
	v_mfma_f32_16x16x32_bf16 v[72:75], v[226:229], v[172:175], v[72:75]
	s_mov_b32 s65, s64
	v_mfma_f32_16x16x32_bf16 v[80:83], v[226:229], v[222:225], v[80:83]
	v_mov_b64_e32 v[228:229], s[66:67]
	v_mov_b64_e32 v[226:227], s[64:65]
	s_waitcnt lgkmcnt(2)
	v_mfma_f32_16x16x32_bf16 v[68:71], v[230:233], v[172:175], v[68:71]
	v_mfma_f32_16x16x32_bf16 v[76:79], v[230:233], v[222:225], v[76:79]
	s_waitcnt lgkmcnt(1)
	v_mfma_f32_16x16x32_bf16 v[56:59], v[234:237], v[172:175], v[56:59]
	v_mfma_f32_16x16x32_bf16 v[64:67], v[234:237], v[222:225], v[64:67]
	s_waitcnt lgkmcnt(0)
	v_mfma_f32_16x16x32_bf16 v[52:55], v[238:241], v[172:175], v[52:55]
	v_mfma_f32_16x16x32_bf16 v[60:63], v[238:241], v[222:225], v[60:63]
	v_mfma_f32_16x16x32_bf16 v[128:131], v[226:229], v[172:175], v[128:131]
	v_mfma_f32_16x16x32_bf16 v[116:119], v[226:229], v[222:225], v[116:119]
	s_branch .LBB0_142

.Lfar_b2:
	s_lshl_b32 s13, s29, 6
	s_mul_i32 s12, s29, 0x2200
	v_add_u32_e32 v171, s12, v139
	ds_read_b128 v[222:225], v171 offset:36864
	ds_read_b128 v[226:229], v171 offset:36928
	ds_read_b128 v[230:233], v171 offset:37952
	ds_read_b128 v[234:237], v171 offset:38016
	s_waitcnt lgkmcnt(3)
	v_mfma_f32_16x16x32_bf16 v[222:225], v[222:225], v[4:7], v[252:255]
	s_waitcnt lgkmcnt(1)
	v_mfma_f32_16x16x32_bf16 v[230:233], v[230:233], v[4:7], v[252:255]
	v_mfma_f32_16x16x32_bf16 v[222:225], v[226:229], v[8:11], v[222:225]
	ds_read_b128 v[226:229], v171 offset:36992
	ds_read_b128 v[238:241], v171 offset:37056
	s_waitcnt lgkmcnt(2)
	v_mfma_f32_16x16x32_bf16 v[230:233], v[234:237], v[8:11], v[230:233]
	ds_read_b128 v[234:237], v171 offset:38080
	ds_read_b128 v[242:245], v171 offset:38144
	s_nop 2
	v_exp_f32_e32 v3, v223
	v_exp_f32_e32 v219, v225
	s_waitcnt lgkmcnt(3)
	v_mfma_f32_16x16x32_bf16 v[226:229], v[226:229], v[12:15], v[252:255]
	v_exp_f32_e32 v225, v231
	s_waitcnt lgkmcnt(2)
	v_mfma_f32_16x16x32_bf16 v[226:229], v[238:241], v[16:19], v[226:229]
	v_add3_u32 v0, s13, v134, v135
	v_exp_f32_e32 v217, v224
	s_waitcnt lgkmcnt(1)
	v_mfma_f32_16x16x32_bf16 v[172:175], v[234:237], v[12:15], v[252:255]
	ds_read_b128 v[234:237], v0 offset:54272
	ds_read_b128 v[238:241], v0 offset:56576
	s_nop 1
	v_exp_f32_e32 v2, v226
	v_exp_f32_e32 v171, v227
	s_waitcnt lgkmcnt(2)
	v_mfma_f32_16x16x32_bf16 v[172:175], v[242:245], v[16:19], v[172:175]
	ds_read_b128 v[242:245], v0 offset:58880
	ds_read_b128 v[246:249], v0 offset:61184
	v_exp_f32_e32 v0, v222
	v_exp_f32_e32 v218, v228
	v_exp_f32_e32 v223, v229
	v_exp_f32_e32 v222, v230
	s_nop 1
	v_exp_f32_e32 v224, v172
	v_exp_f32_e32 v226, v173
	v_exp_f32_e32 v227, v232
	v_exp_f32_e32 v228, v174
	v_exp_f32_e32 v229, v233
	v_exp_f32_e32 v230, v175
	v_cvt_pk_bf16_f32 v172, v0, v3
	v_cvt_pk_bf16_f32 v173, v217, v219
	v_cvt_pk_bf16_f32 v174, v222, v225
	v_cvt_pk_bf16_f32 v175, v227, v229
	v_cvt_pk_bf16_f32 v222, v2, v171
	v_cvt_pk_bf16_f32 v223, v218, v223
	v_cvt_pk_bf16_f32 v224, v224, v226
	v_cvt_pk_bf16_f32 v225, v228, v230
	v_add3_u32 v0, s13, v135, v134
	v_add_u32_e32 v2, 0x10100, v0
	ds_read_b128 v[226:229], v0 offset:63488
	ds_read_b128 v[230:233], v2
	v_add_u32_e32 v2, 0x10a00, v0
	v_add_u32_e32 v0, 0x11300, v0
	s_waitcnt lgkmcnt(5)
	v_mfma_f32_16x16x32_bf16 v[104:107], v[234:237], v[172:175], v[104:107]
	v_mfma_f32_16x16x32_bf16 v[112:115], v[234:237], v[222:225], v[112:115]
	ds_read_b128 v[234:237], v2
	s_waitcnt lgkmcnt(5)
	v_mfma_f32_16x16x32_bf16 v[100:103], v[238:241], v[172:175], v[100:103]
	v_mfma_f32_16x16x32_bf16 v[108:111], v[238:241], v[222:225], v[108:111]
	ds_read_b128 v[238:241], v0
	s_waitcnt lgkmcnt(5)
	v_mfma_f32_16x16x32_bf16 v[88:91], v[242:245], v[172:175], v[88:91]
	v_mfma_f32_16x16x32_bf16 v[96:99], v[242:245], v[222:225], v[96:99]
	v_mfma_f32_16x16x32_bf16 v[84:87], v[246:249], v[172:175], v[84:87]
	v_mfma_f32_16x16x32_bf16 v[92:95], v[246:249], v[222:225], v[92:95]
	s_mov_b32 s66, s64
	s_mov_b32 s67, s64
	s_waitcnt lgkmcnt(3)
	v_mfma_f32_16x16x32_bf16 v[72:75], v[226:229], v[172:175], v[72:75]
	s_mov_b32 s65, s64
	v_mfma_f32_16x16x32_bf16 v[80:83], v[226:229], v[222:225], v[80:83]
	v_mov_b64_e32 v[228:229], s[66:67]
	v_mov_b64_e32 v[226:227], s[64:65]
	s_waitcnt lgkmcnt(2)
	v_mfma_f32_16x16x32_bf16 v[68:71], v[230:233], v[172:175], v[68:71]
	v_mfma_f32_16x16x32_bf16 v[76:79], v[230:233], v[222:225], v[76:79]
	s_waitcnt lgkmcnt(1)
	v_mfma_f32_16x16x32_bf16 v[56:59], v[234:237], v[172:175], v[56:59]
	v_mfma_f32_16x16x32_bf16 v[64:67], v[234:237], v[222:225], v[64:67]
	s_waitcnt lgkmcnt(0)
	v_mfma_f32_16x16x32_bf16 v[52:55], v[238:241], v[172:175], v[52:55]
	v_mfma_f32_16x16x32_bf16 v[60:63], v[238:241], v[222:225], v[60:63]
	v_mfma_f32_16x16x32_bf16 v[128:131], v[226:229], v[172:175], v[128:131]
	v_mfma_f32_16x16x32_bf16 v[116:119], v[226:229], v[222:225], v[116:119]
	s_branch .LBB0_168
